# v068 + G_DN K-loop fully saddr-form: kstep/hstep folded into per-tile precomputed 32-bit offsets, no per-iteration address VALU, base advance moved below piece 2
# baseline (speedup 1.0000x reference)
.LBB0_1264:
	s_ashr_i32 s17, s16, 31
	s_lshl_b64 s[24:25], s[16:17], 22
	s_add_u32 s24, s51, s24
	s_addc_u32 s25, s58, s25
	s_and_b64 s[30:31], s[40:41], exec
	s_cselect_b32 s12, s25, s43
	s_cselect_b32 s17, s24, s42
	s_ashr_i32 s5, s4, 31
	s_lshl_b64 s[30:31], s[4:5], 22
	s_add_u32 s30, s27, s30
	s_addc_u32 s31, s50, s31
	s_and_b64 s[52:53], s[40:41], exec
	s_cselect_b32 s5, s31, s45
	s_cselect_b32 s18, s30, s44
	s_add_u32 s42, s42, 0x200080
	s_addc_u32 s43, s43, 0
	s_add_u32 s20, s44, 0x100
	v_mov_b32_e32 v0, 0
	s_addc_u32 s28, s45, 0
	s_mov_b32 s33, -2
	v_mov_b32_e32 v1, v0
	v_mov_b32_e32 v2, v0
	v_mov_b32_e32 v3, v0
	v_mov_b32_e32 v4, v0
	v_mov_b32_e32 v5, v0
	v_mov_b32_e32 v6, v0
	v_mov_b32_e32 v7, v0
	v_mov_b32_e32 v16, v0
	v_mov_b32_e32 v17, v0
	v_mov_b32_e32 v18, v0
	v_mov_b32_e32 v19, v0
	v_mov_b32_e32 v20, v0
	v_mov_b32_e32 v21, v0
	v_mov_b32_e32 v22, v0
	v_mov_b32_e32 v23, v0
	v_mov_b32_e32 v32, v0
	v_mov_b32_e32 v33, v0
	v_mov_b32_e32 v34, v0
	v_mov_b32_e32 v35, v0
	v_mov_b32_e32 v36, v0
	v_mov_b32_e32 v37, v0
	v_mov_b32_e32 v38, v0
	v_mov_b32_e32 v39, v0
	v_mov_b32_e32 v48, v0
	v_mov_b32_e32 v49, v0
	v_mov_b32_e32 v50, v0
	v_mov_b32_e32 v51, v0
	v_mov_b32_e32 v52, v0
	v_mov_b32_e32 v53, v0
	v_mov_b32_e32 v54, v0
	v_mov_b32_e32 v55, v0
	v_mov_b32_e32 v8, v0
	v_mov_b32_e32 v9, v0
	v_mov_b32_e32 v10, v0
	v_mov_b32_e32 v11, v0
	v_mov_b32_e32 v12, v0
	v_mov_b32_e32 v13, v0
	v_mov_b32_e32 v14, v0
	v_mov_b32_e32 v15, v0
	v_mov_b32_e32 v24, v0
	v_mov_b32_e32 v25, v0
	v_mov_b32_e32 v26, v0
	v_mov_b32_e32 v27, v0
	v_mov_b32_e32 v28, v0
	v_mov_b32_e32 v29, v0
	v_mov_b32_e32 v30, v0
	v_mov_b32_e32 v31, v0
	v_mov_b32_e32 v40, v0
	v_mov_b32_e32 v41, v0
	v_mov_b32_e32 v42, v0
	v_mov_b32_e32 v43, v0
	v_mov_b32_e32 v44, v0
	v_mov_b32_e32 v45, v0
	v_mov_b32_e32 v46, v0
	v_mov_b32_e32 v47, v0
	v_mov_b32_e32 v56, v0
	v_mov_b32_e32 v57, v0
	v_mov_b32_e32 v58, v0
	v_mov_b32_e32 v59, v0
	v_mov_b32_e32 v60, v0
	v_mov_b32_e32 v61, v0
	v_mov_b32_e32 v62, v0
	v_mov_b32_e32 v63, v0
	v_mov_b32_e32 v64, v0
	v_mov_b32_e32 v65, v0
	v_mov_b32_e32 v66, v0
	v_mov_b32_e32 v67, v0
	v_mov_b32_e32 v68, v0
	v_mov_b32_e32 v69, v0
	v_mov_b32_e32 v70, v0
	v_mov_b32_e32 v71, v0
	v_mov_b32_e32 v80, v0
	v_mov_b32_e32 v81, v0
	v_mov_b32_e32 v82, v0
	v_mov_b32_e32 v83, v0
	v_mov_b32_e32 v84, v0
	v_mov_b32_e32 v85, v0
	v_mov_b32_e32 v86, v0
	v_mov_b32_e32 v87, v0
	v_mov_b32_e32 v98, v0
	v_mov_b32_e32 v99, v0
	v_mov_b32_e32 v100, v0
	v_mov_b32_e32 v101, v0
	v_mov_b32_e32 v102, v0
	v_mov_b32_e32 v103, v0
	v_mov_b32_e32 v104, v0
	v_mov_b32_e32 v105, v0
	v_mov_b32_e32 v114, v0
	v_mov_b32_e32 v115, v0
	v_mov_b32_e32 v116, v0
	v_mov_b32_e32 v117, v0
	v_mov_b32_e32 v118, v0
	v_mov_b32_e32 v119, v0
	v_mov_b32_e32 v120, v0
	v_mov_b32_e32 v121, v0
	v_mov_b32_e32 v72, v0
	v_mov_b32_e32 v73, v0
	v_mov_b32_e32 v74, v0
	v_mov_b32_e32 v75, v0
	v_mov_b32_e32 v76, v0
	v_mov_b32_e32 v77, v0
	v_mov_b32_e32 v78, v0
	v_mov_b32_e32 v79, v0
	v_mov_b32_e32 v88, v0
	v_mov_b32_e32 v89, v0
	v_mov_b32_e32 v90, v0
	v_mov_b32_e32 v91, v0
	v_mov_b32_e32 v92, v0
	v_mov_b32_e32 v93, v0
	v_mov_b32_e32 v94, v0
	v_mov_b32_e32 v95, v0
	v_mov_b32_e32 v106, v0
	v_mov_b32_e32 v107, v0
	v_mov_b32_e32 v108, v0
	v_mov_b32_e32 v109, v0
	v_mov_b32_e32 v110, v0
	v_mov_b32_e32 v111, v0
	v_mov_b32_e32 v112, v0
	v_mov_b32_e32 v113, v0
	v_mov_b32_e32 v122, v0
	v_mov_b32_e32 v123, v0
	v_mov_b32_e32 v124, v0
	v_mov_b32_e32 v125, v0
	v_mov_b32_e32 v126, v0
	v_mov_b32_e32 v127, v0
	v_mov_b32_e32 v128, v0
	v_mov_b32_e32 v129, v0
	v_add_u32_e32 v222, 0x80, v96
	v_add_u32_e32 v223, 0x80, v134
	v_add_u32_e32 v224, 0x80, v138
	v_add_u32_e32 v225, 0x80, v136
	v_add_u32_e32 v226, 0x200000, v138
	v_add_u32_e32 v227, 0x200000, v136

.Lrx_G_DN_0:
	s_waitcnt vmcnt(44)
	s_waitcnt lgkmcnt(0)
	s_setprio 1
	s_barrier
	v_mfma_f32_16x16x32_bf16 v[126:129], v[144:147], v[184:187], v[126:129]
	v_mfma_f32_16x16x32_bf16 v[122:125], v[160:163], v[184:187], v[122:125]
	v_mfma_f32_16x16x32_bf16 v[110:113], v[144:147], v[192:195], v[110:113]
	v_mfma_f32_16x16x32_bf16 v[106:109], v[160:163], v[192:195], v[106:109]
	v_mfma_f32_16x16x32_bf16 v[92:95], v[144:147], v[202:205], v[92:95]
	v_mfma_f32_16x16x32_bf16 v[88:91], v[160:163], v[202:205], v[88:91]
	v_mfma_f32_16x16x32_bf16 v[76:79], v[144:147], v[214:217], v[76:79]
	v_mfma_f32_16x16x32_bf16 v[72:75], v[160:163], v[214:217], v[72:75]
	v_mfma_f32_16x16x32_bf16 v[126:129], v[154:157], v[188:191], v[126:129]
	v_mfma_f32_16x16x32_bf16 v[122:125], v[164:167], v[188:191], v[122:125]
	v_mfma_f32_16x16x32_bf16 v[110:113], v[154:157], v[196:199], v[110:113]
	v_mfma_f32_16x16x32_bf16 v[106:109], v[164:167], v[196:199], v[106:109]
	v_mfma_f32_16x16x32_bf16 v[92:95], v[154:157], v[210:213], v[92:95]
	v_mfma_f32_16x16x32_bf16 v[88:91], v[164:167], v[210:213], v[88:91]
	v_mfma_f32_16x16x32_bf16 v[76:79], v[154:157], v[218:221], v[76:79]
	v_mfma_f32_16x16x32_bf16 v[72:75], v[164:167], v[218:221], v[72:75]
	v_mfma_f32_16x16x32_bf16 v[118:121], v[168:171], v[184:187], v[118:121]
	v_mfma_f32_16x16x32_bf16 v[114:117], v[176:179], v[184:187], v[114:117]
	v_mfma_f32_16x16x32_bf16 v[102:105], v[168:171], v[192:195], v[102:105]
	v_mfma_f32_16x16x32_bf16 v[98:101], v[176:179], v[192:195], v[98:101]
	v_mfma_f32_16x16x32_bf16 v[84:87], v[168:171], v[202:205], v[84:87]
	v_mfma_f32_16x16x32_bf16 v[80:83], v[176:179], v[202:205], v[80:83]
	v_mfma_f32_16x16x32_bf16 v[68:71], v[168:171], v[214:217], v[68:71]
	v_mfma_f32_16x16x32_bf16 v[64:67], v[176:179], v[214:217], v[64:67]
	v_mfma_f32_16x16x32_bf16 v[118:121], v[172:175], v[188:191], v[118:121]
	v_mfma_f32_16x16x32_bf16 v[114:117], v[180:183], v[188:191], v[114:117]
	v_mfma_f32_16x16x32_bf16 v[102:105], v[172:175], v[196:199], v[102:105]
	v_mfma_f32_16x16x32_bf16 v[98:101], v[180:183], v[196:199], v[98:101]
	v_mfma_f32_16x16x32_bf16 v[84:87], v[172:175], v[210:213], v[84:87]
	v_mfma_f32_16x16x32_bf16 v[80:83], v[180:183], v[210:213], v[80:83]
	v_mfma_f32_16x16x32_bf16 v[68:71], v[172:175], v[218:221], v[68:71]
	v_mfma_f32_16x16x32_bf16 v[64:67], v[180:183], v[218:221], v[64:67]
	s_barrier
	s_setprio 0
	s_add_i32 s54, s54, s75
	s_mov_b32 m0, s54
	ds_read_b128 v[184:187], v159 offset:16384
	ds_read_b128 v[188:191], v159 offset:17408
	ds_read_b128 v[192:195], v159 offset:18432
	ds_read_b128 v[196:199], v159 offset:19456
	ds_read_b128 v[202:205], v159 offset:20480
	ds_read_b128 v[210:213], v159 offset:21504
	ds_read_b128 v[214:217], v159 offset:22528
	ds_read_b128 v[218:221], v159 offset:23552
	global_load_lds_dwordx4 v96, s[44:45]
	s_add_i32 m0, s54, 0x2000
	s_add_u32 s54, s44, 0x200000
	s_addc_u32 s55, s45, 0
	s_add_i32 s35, s35, s75
	global_load_lds_dwordx4 v134, s[44:45]
	s_mov_b32 m0, s35
	s_nop 0
	global_load_lds_dwordx4 v96, s[54:55]
	s_add_i32 m0, s35, 0x2000
	s_nop 0
	global_load_lds_dwordx4 v134, s[54:55]
	s_mov_b32 m0, s59
	s_nop 0
	global_load_lds_dwordx4 v138, s[52:53]
	s_mov_b32 m0, s68
	s_nop 0
	global_load_lds_dwordx4 v136, s[52:53]
	v_cmp_ne_u32_e32 vcc, 0, v243
	s_cbranch_vccnz .Lrx_G_DN_1
	s_waitcnt vmcnt(8)
.Lrx_G_DN_1:
	s_waitcnt vmcnt(44)
	v_mov_b32_e32 v243, 0
	s_waitcnt lgkmcnt(0)
	s_setprio 1
	s_barrier
	v_mfma_f32_16x16x32_bf16 v[60:63], v[144:147], v[184:187], v[60:63]
	v_mfma_f32_16x16x32_bf16 v[56:59], v[160:163], v[184:187], v[56:59]
	v_mfma_f32_16x16x32_bf16 v[44:47], v[144:147], v[192:195], v[44:47]
	v_mfma_f32_16x16x32_bf16 v[40:43], v[160:163], v[192:195], v[40:43]
	v_mfma_f32_16x16x32_bf16 v[28:31], v[144:147], v[202:205], v[28:31]
	v_mfma_f32_16x16x32_bf16 v[24:27], v[160:163], v[202:205], v[24:27]
	v_mfma_f32_16x16x32_bf16 v[12:15], v[144:147], v[214:217], v[12:15]
	v_mfma_f32_16x16x32_bf16 v[8:11], v[160:163], v[214:217], v[8:11]
	v_mfma_f32_16x16x32_bf16 v[60:63], v[154:157], v[188:191], v[60:63]
	v_mfma_f32_16x16x32_bf16 v[56:59], v[164:167], v[188:191], v[56:59]
	v_mfma_f32_16x16x32_bf16 v[44:47], v[154:157], v[196:199], v[44:47]
	v_mfma_f32_16x16x32_bf16 v[40:43], v[164:167], v[196:199], v[40:43]
	v_mfma_f32_16x16x32_bf16 v[28:31], v[154:157], v[210:213], v[28:31]
	v_mfma_f32_16x16x32_bf16 v[24:27], v[164:167], v[210:213], v[24:27]
	v_mfma_f32_16x16x32_bf16 v[12:15], v[154:157], v[218:221], v[12:15]
	v_mfma_f32_16x16x32_bf16 v[8:11], v[164:167], v[218:221], v[8:11]
	v_mfma_f32_16x16x32_bf16 v[52:55], v[168:171], v[184:187], v[52:55]
	v_mfma_f32_16x16x32_bf16 v[48:51], v[176:179], v[184:187], v[48:51]
	v_mfma_f32_16x16x32_bf16 v[36:39], v[168:171], v[192:195], v[36:39]
	v_mfma_f32_16x16x32_bf16 v[32:35], v[176:179], v[192:195], v[32:35]
	v_mfma_f32_16x16x32_bf16 v[20:23], v[168:171], v[202:205], v[20:23]
	v_mfma_f32_16x16x32_bf16 v[16:19], v[176:179], v[202:205], v[16:19]
	v_mfma_f32_16x16x32_bf16 v[4:7], v[168:171], v[214:217], v[4:7]
	v_mfma_f32_16x16x32_bf16 v[0:3], v[176:179], v[214:217], v[0:3]
	v_mfma_f32_16x16x32_bf16 v[52:55], v[172:175], v[188:191], v[52:55]
	v_mfma_f32_16x16x32_bf16 v[48:51], v[180:183], v[188:191], v[48:51]
	v_mfma_f32_16x16x32_bf16 v[36:39], v[172:175], v[196:199], v[36:39]
	v_mfma_f32_16x16x32_bf16 v[32:35], v[180:183], v[196:199], v[32:35]
	v_mfma_f32_16x16x32_bf16 v[20:23], v[172:175], v[210:213], v[20:23]
	v_mfma_f32_16x16x32_bf16 v[16:19], v[180:183], v[210:213], v[16:19]
	v_mfma_f32_16x16x32_bf16 v[4:7], v[172:175], v[218:221], v[4:7]
	v_mfma_f32_16x16x32_bf16 v[0:3], v[180:183], v[218:221], v[0:3]
	s_barrier
	s_setprio 0
	s_add_i32 s35, 0, 0x18000
	s_add_i32 s54, 0, 0x1c000
	v_add_u32_e32 v164, s35, v153
	v_add_u32_e32 v180, s54, v153
	ds_read_b128 v[144:147], v164
	ds_read_b128 v[154:157], v164 offset:1024
	ds_read_b128 v[160:163], v164 offset:2048
	ds_read_b128 v[164:167], v164 offset:3072
	ds_read_b128 v[168:171], v180
	ds_read_b128 v[172:175], v180 offset:1024
	ds_read_b128 v[176:179], v180 offset:2048
	ds_read_b128 v[180:183], v180 offset:3072
	s_mov_b32 m0, s69
	ds_read_b128 v[184:187], v159 offset:32768
	ds_read_b128 v[188:191], v159 offset:33792
	ds_read_b128 v[192:195], v159 offset:34816
	ds_read_b128 v[196:199], v159 offset:35840
	ds_read_b128 v[202:205], v159 offset:36864
	ds_read_b128 v[210:213], v159 offset:37888
	ds_read_b128 v[214:217], v159 offset:38912
	ds_read_b128 v[218:221], v159 offset:39936
	global_load_lds_dwordx4 v226, s[52:53]
	s_mov_b32 m0, s79
	s_nop 0
	global_load_lds_dwordx4 v227, s[52:53]
	s_waitcnt vmcnt(8)
	s_waitcnt lgkmcnt(0)
	s_setprio 1
	s_barrier
	v_mfma_f32_16x16x32_bf16 v[126:129], v[144:147], v[184:187], v[126:129]
	v_mfma_f32_16x16x32_bf16 v[122:125], v[160:163], v[184:187], v[122:125]
	v_mfma_f32_16x16x32_bf16 v[110:113], v[144:147], v[192:195], v[110:113]
	v_mfma_f32_16x16x32_bf16 v[106:109], v[160:163], v[192:195], v[106:109]
	v_mfma_f32_16x16x32_bf16 v[92:95], v[144:147], v[202:205], v[92:95]
	v_mfma_f32_16x16x32_bf16 v[88:91], v[160:163], v[202:205], v[88:91]
	v_mfma_f32_16x16x32_bf16 v[76:79], v[144:147], v[214:217], v[76:79]
	v_mfma_f32_16x16x32_bf16 v[72:75], v[160:163], v[214:217], v[72:75]
	v_mfma_f32_16x16x32_bf16 v[126:129], v[154:157], v[188:191], v[126:129]
	v_mfma_f32_16x16x32_bf16 v[122:125], v[164:167], v[188:191], v[122:125]
	v_mfma_f32_16x16x32_bf16 v[110:113], v[154:157], v[196:199], v[110:113]
	v_mfma_f32_16x16x32_bf16 v[106:109], v[164:167], v[196:199], v[106:109]
	v_mfma_f32_16x16x32_bf16 v[92:95], v[154:157], v[210:213], v[92:95]
	v_mfma_f32_16x16x32_bf16 v[88:91], v[164:167], v[210:213], v[88:91]
	v_mfma_f32_16x16x32_bf16 v[76:79], v[154:157], v[218:221], v[76:79]
	v_mfma_f32_16x16x32_bf16 v[72:75], v[164:167], v[218:221], v[72:75]
	v_mfma_f32_16x16x32_bf16 v[118:121], v[168:171], v[184:187], v[118:121]
	v_mfma_f32_16x16x32_bf16 v[114:117], v[176:179], v[184:187], v[114:117]
	v_mfma_f32_16x16x32_bf16 v[102:105], v[168:171], v[192:195], v[102:105]
	v_mfma_f32_16x16x32_bf16 v[98:101], v[176:179], v[192:195], v[98:101]
	v_mfma_f32_16x16x32_bf16 v[84:87], v[168:171], v[202:205], v[84:87]
	v_mfma_f32_16x16x32_bf16 v[80:83], v[176:179], v[202:205], v[80:83]
	v_mfma_f32_16x16x32_bf16 v[68:71], v[168:171], v[214:217], v[68:71]
	v_mfma_f32_16x16x32_bf16 v[64:67], v[176:179], v[214:217], v[64:67]
	v_mfma_f32_16x16x32_bf16 v[118:121], v[172:175], v[188:191], v[118:121]
	v_mfma_f32_16x16x32_bf16 v[114:117], v[180:183], v[188:191], v[114:117]
	v_mfma_f32_16x16x32_bf16 v[102:105], v[172:175], v[196:199], v[102:105]
	v_mfma_f32_16x16x32_bf16 v[98:101], v[180:183], v[196:199], v[98:101]
	v_mfma_f32_16x16x32_bf16 v[84:87], v[172:175], v[210:213], v[84:87]
	v_mfma_f32_16x16x32_bf16 v[80:83], v[180:183], v[210:213], v[80:83]
	v_mfma_f32_16x16x32_bf16 v[68:71], v[172:175], v[218:221], v[68:71]
	v_mfma_f32_16x16x32_bf16 v[64:67], v[180:183], v[218:221], v[64:67]
	s_barrier
	s_setprio 0
	s_add_i32 s35, s35, s75
	s_mov_b32 m0, s35
	ds_read_b128 v[184:187], v159 offset:49152
	ds_read_b128 v[188:191], v159 offset:50176
	ds_read_b128 v[192:195], v159 offset:51200
	ds_read_b128 v[196:199], v159 offset:52224
	ds_read_b128 v[202:205], v159 offset:53248
	ds_read_b128 v[210:213], v159 offset:54272
	ds_read_b128 v[214:217], v159 offset:55296
	ds_read_b128 v[218:221], v159 offset:56320
	global_load_lds_dwordx4 v222, s[44:45]
	s_add_i32 m0, s35, 0x2000
	s_add_i32 s35, s54, s75
	global_load_lds_dwordx4 v223, s[44:45]
	s_add_u32 s44, s44, 0x200080
	s_addc_u32 s45, s45, 0
	s_mov_b32 m0, s35
	s_nop 0
	global_load_lds_dwordx4 v96, s[44:45]
	s_add_i32 m0, s35, 0x2000
	s_nop 0
	global_load_lds_dwordx4 v134, s[44:45]
	s_mov_b32 m0, s10
	s_nop 0
	global_load_lds_dwordx4 v224, s[52:53]
	s_mov_b32 m0, s77
	s_nop 0
	global_load_lds_dwordx4 v225, s[52:53]
	s_waitcnt vmcnt(8)
	s_waitcnt lgkmcnt(0)
	s_setprio 1
	s_barrier
	v_mfma_f32_16x16x32_bf16 v[60:63], v[144:147], v[184:187], v[60:63]
	v_mfma_f32_16x16x32_bf16 v[56:59], v[160:163], v[184:187], v[56:59]
	v_mfma_f32_16x16x32_bf16 v[44:47], v[144:147], v[192:195], v[44:47]
	v_mfma_f32_16x16x32_bf16 v[40:43], v[160:163], v[192:195], v[40:43]
	v_mfma_f32_16x16x32_bf16 v[28:31], v[144:147], v[202:205], v[28:31]
	v_mfma_f32_16x16x32_bf16 v[24:27], v[160:163], v[202:205], v[24:27]
	v_mfma_f32_16x16x32_bf16 v[12:15], v[144:147], v[214:217], v[12:15]
	v_mfma_f32_16x16x32_bf16 v[8:11], v[160:163], v[214:217], v[8:11]
	v_mfma_f32_16x16x32_bf16 v[60:63], v[154:157], v[188:191], v[60:63]
	v_mfma_f32_16x16x32_bf16 v[56:59], v[164:167], v[188:191], v[56:59]
	v_mfma_f32_16x16x32_bf16 v[44:47], v[154:157], v[196:199], v[44:47]
	v_mfma_f32_16x16x32_bf16 v[40:43], v[164:167], v[196:199], v[40:43]
	v_mfma_f32_16x16x32_bf16 v[28:31], v[154:157], v[210:213], v[28:31]
	v_mfma_f32_16x16x32_bf16 v[24:27], v[164:167], v[210:213], v[24:27]
	v_mfma_f32_16x16x32_bf16 v[12:15], v[154:157], v[218:221], v[12:15]
	v_mfma_f32_16x16x32_bf16 v[8:11], v[164:167], v[218:221], v[8:11]
	v_mfma_f32_16x16x32_bf16 v[52:55], v[168:171], v[184:187], v[52:55]
	v_mfma_f32_16x16x32_bf16 v[48:51], v[176:179], v[184:187], v[48:51]
	v_mfma_f32_16x16x32_bf16 v[36:39], v[168:171], v[192:195], v[36:39]
	v_mfma_f32_16x16x32_bf16 v[32:35], v[176:179], v[192:195], v[32:35]
	v_mfma_f32_16x16x32_bf16 v[20:23], v[168:171], v[202:205], v[20:23]
	v_mfma_f32_16x16x32_bf16 v[16:19], v[176:179], v[202:205], v[16:19]
	v_mfma_f32_16x16x32_bf16 v[4:7], v[168:171], v[214:217], v[4:7]
	v_mfma_f32_16x16x32_bf16 v[0:3], v[176:179], v[214:217], v[0:3]
	v_mfma_f32_16x16x32_bf16 v[52:55], v[172:175], v[188:191], v[52:55]
	v_mfma_f32_16x16x32_bf16 v[48:51], v[180:183], v[188:191], v[48:51]
	v_mfma_f32_16x16x32_bf16 v[36:39], v[172:175], v[196:199], v[36:39]
	v_mfma_f32_16x16x32_bf16 v[32:35], v[180:183], v[196:199], v[32:35]
	v_mfma_f32_16x16x32_bf16 v[20:23], v[172:175], v[210:213], v[20:23]
	v_mfma_f32_16x16x32_bf16 v[16:19], v[180:183], v[210:213], v[16:19]
	v_mfma_f32_16x16x32_bf16 v[4:7], v[172:175], v[218:221], v[4:7]
	v_mfma_f32_16x16x32_bf16 v[0:3], v[180:183], v[218:221], v[0:3]
	s_barrier
	s_setprio 0
	s_add_i32 s33, s33, 2
	s_add_u32 s42, s42, 0x100
	s_addc_u32 s43, s43, 0
	s_add_u32 s20, s20, 0x100
	s_addc_u32 s28, s28, 0
	s_cmpk_gt_u32 s33, 0x7d
	s_cbranch_scc0 .LBB0_1265
	v_mov_b32_e32 v243, 1
	v_readlane_b32 s6, v251, 54
	v_readlane_b32 s7, v251, 55
	s_and_b64 vcc, exec, s[6:7]
	s_movk_i32 s53, 0x6000
	s_cbranch_vccz .LBB0_1268
	s_barrier
